# final-norm queue: next round's queue atomic overlaps this round's loads (result copied after the first load wait)
# baseline (speedup 1.0000x reference)
.LBB0_2376:
	s_lshl_b32 s11, s30, 5
	s_and_b32 s11, s11, 0xe0
	s_lshl_b32 s10, s31, 8
	s_add_i32 s12, s11, s26
	s_add_i32 s16, s12, s10
	s_ashr_i32 s10, s16, 4
	s_and_b32 s13, s10, -16
	s_lshr_b32 s10, s12, 3
	s_ashr_i32 s17, s16, 31
	v_and_or_b32 v18, s10, 14, v42
	s_lshl_b64 s[10:11], s[16:17], 6
	v_lshl_add_u64 v[20:21], v[22:23], 0, s[10:11]
	global_load_dwordx4 v[56:59], v[20:21], off
	s_lshl_b32 s10, s12, 7
	s_lshl_b32 s11, s12, 6
	s_lshl_b32 s12, s12, 2
	s_and_b32 s12, s12, 32
	s_and_b32 s11, s11, 0x300
	v_mov_b32_e32 v20, s12
	v_lshlrev_b32_e32 v55, 10, v18
	v_or_b32_e32 v18, s13, v210
	s_and_b32 s10, s10, 0x4000
	v_bitop3_b32 v20, s11, v20, v43 bitop3:0x36
	v_ashrrev_i32_e32 v19, 31, v18
	v_or3_b32 v194, s10, v20, v55
	v_lshlrev_b64 v[18:19], 15, v[18:19]
	v_lshl_add_u64 v[20:21], s[34:35], 0, v[194:195]
	v_lshl_add_u64 v[24:25], v[20:21], 0, v[18:19]
	global_load_dwordx2 v[68:69], v[24:25], off nt
	v_or_b32_e32 v24, s13, v44
	v_or_b32_e32 v28, s13, v45
	v_or_b32_e32 v32, s13, v46
	v_ashrrev_i32_e32 v25, 31, v24
	v_ashrrev_i32_e32 v29, 31, v28
	v_ashrrev_i32_e32 v33, 31, v32
	s_or_b32 s14, s16, 1
	v_lshlrev_b64 v[24:25], 15, v[24:25]
	v_lshlrev_b64 v[28:29], 15, v[28:29]
	v_lshlrev_b64 v[32:33], 15, v[32:33]
	s_ashr_i32 s15, s14, 31
	v_lshl_add_u64 v[26:27], v[20:21], 0, v[24:25]
	v_lshl_add_u64 v[30:31], v[20:21], 0, v[28:29]
	v_lshl_add_u64 v[20:21], v[20:21], 0, v[32:33]
	s_lshl_b64 s[10:11], s[14:15], 6
	global_load_dwordx2 v[70:71], v[26:27], off nt
	global_load_dwordx2 v[72:73], v[30:31], off nt
	global_load_dwordx2 v[74:75], v[20:21], off nt
	v_lshl_add_u64 v[20:21], v[22:23], 0, s[10:11]
	s_lshl_b32 s11, s16, 2
	s_lshl_b32 s10, s14, 6
	s_and_b32 s11, s11, 32
	s_and_b32 s10, s10, 0x340
	v_mov_b32_e32 v84, s11
	v_bitop3_b32 v26, s10, v84, v43 bitop3:0x36
	s_lshl_b32 s10, s16, 7
	s_and_b32 s19, s10, 0x4000
	v_or3_b32 v194, s19, v26, v55
	v_lshl_add_u64 v[26:27], s[34:35], 0, v[194:195]
	v_lshl_add_u64 v[30:31], v[26:27], 0, v[18:19]
	global_load_dwordx4 v[60:63], v[20:21], off
	global_load_dwordx2 v[76:77], v[30:31], off nt
	s_or_b32 s12, s16, 2
	s_ashr_i32 s13, s12, 31
	v_lshl_add_u64 v[20:21], v[26:27], 0, v[24:25]
	s_lshl_b64 s[10:11], s[12:13], 6
	v_lshl_add_u64 v[30:31], v[26:27], 0, v[28:29]
	v_lshl_add_u64 v[26:27], v[26:27], 0, v[32:33]
	global_load_dwordx2 v[78:79], v[20:21], off nt
	global_load_dwordx2 v[80:81], v[30:31], off nt
	global_load_dwordx2 v[38:39], v[26:27], off nt
	v_lshl_add_u64 v[20:21], v[22:23], 0, s[10:11]
	s_lshl_b32 s10, s12, 6
	s_and_b32 s10, s10, 0x380
	v_bitop3_b32 v26, s10, v84, v43 bitop3:0x36
	v_or3_b32 v194, s19, v26, v55
	v_lshl_add_u64 v[26:27], s[34:35], 0, v[194:195]
	v_lshl_add_u64 v[30:31], v[26:27], 0, v[18:19]
	global_load_dwordx4 v[64:67], v[20:21], off
	global_load_dwordx2 v[40:41], v[30:31], off nt
	s_or_b32 s10, s16, 3
	s_ashr_i32 s11, s10, 31
	v_lshl_add_u64 v[20:21], v[26:27], 0, v[24:25]
	v_lshl_add_u64 v[82:83], v[26:27], 0, v[32:33]
	s_lshl_b64 s[30:31], s[10:11], 6
	v_lshl_add_u64 v[30:31], v[26:27], 0, v[28:29]
	global_load_dwordx2 v[36:37], v[20:21], off nt
	global_load_dwordx2 v[34:35], v[30:31], off nt
	global_load_dwordx2 v[26:27], v[82:83], off nt
	v_lshl_add_u64 v[82:83], v[22:23], 0, s[30:31]
	s_lshl_b32 s30, s10, 6
	s_and_b32 s30, s30, 0x3c0
	v_bitop3_b32 v20, s30, v84, v43 bitop3:0x36
	v_or3_b32 v194, s19, v20, v55
	v_lshl_add_u64 v[84:85], s[34:35], 0, v[194:195]
	v_cmp_lt_i32_e32 vcc, v51, v52
	v_lshl_add_u64 v[86:87], v[84:85], 0, v[18:19]
	global_load_dwordx4 v[18:21], v[82:83], off
	global_load_dwordx2 v[30:31], v[86:87], off nt
	v_lshl_add_u64 v[82:83], v[84:85], 0, v[24:25]
	v_cndmask_b32_e32 v24, v50, v51, vcc
	v_lshlrev_b32_e32 v55, 2, v24
	s_waitcnt vmcnt(16)
	v_mov_b32_e32 v54, v254
	v_mov_b32_e32 v24, v57
	v_mov_b32_e32 v25, v58
	v_mov_b32_e32 v57, v59
	v_pk_add_f32 v[24:25], v[24:25], v[56:57]
	v_cmp_lt_i32_e32 vcc, v53, v52
	v_add_f32_e32 v24, v24, v25
	ds_bpermute_b32 v25, v55, v24
	v_lshl_add_u64 v[56:57], v[84:85], 0, v[28:29]
	v_cndmask_b32_e32 v28, v50, v53, vcc
	v_lshlrev_b32_e32 v86, 2, v28
	v_lshl_add_u64 v[58:59], v[84:85], 0, v[32:33]
	s_waitcnt lgkmcnt(0)
	v_add_f32_e32 v87, v24, v25
	ds_bpermute_b32 v88, v86, v87
	global_load_dwordx2 v[32:33], v[82:83], off nt
	global_load_dwordx2 v[28:29], v[56:57], off nt
	global_load_dwordx2 v[24:25], v[58:59], off nt
	s_lshl_b64 s[16:17], s[16:17], 12
	s_lshl_b64 s[14:15], s[14:15], 12
	s_waitcnt vmcnt(18)
	v_and_b32_e32 v57, 0xffff0000, v68
	s_waitcnt lgkmcnt(0)
	v_add_f32_e32 v56, v87, v88
	v_fmamk_f32 v56, v56, 0x3a800000, v49
	v_rsq_f32_e32 v82, v56
	v_lshlrev_b32_e32 v56, 16, v68
	v_lshlrev_b32_e32 v58, 16, v69
	v_and_b32_e32 v59, 0xffff0000, v69
	v_pk_mul_f32 v[56:57], v[82:83], v[56:57] op_sel_hi:[0,1]
	v_pk_mul_f32 v[58:59], v[82:83], v[58:59] op_sel_hi:[0,1]
	v_pk_mul_f32 v[58:59], v[4:5], v[58:59]
	v_pk_mul_f32 v[56:57], v[2:3], v[56:57]
	v_lshl_add_u64 v[68:69], v[0:1], 0, s[16:17]
	global_store_dwordx4 v[68:69], v[56:59], off nt
	s_lshl_b64 s[12:13], s[12:13], 12
	s_lshl_b64 s[10:11], s[10:11], 12
	s_waitcnt vmcnt(18)
	v_lshlrev_b32_e32 v56, 16, v70
	v_and_b32_e32 v57, 0xffff0000, v70
	v_lshlrev_b32_e32 v58, 16, v71
	v_and_b32_e32 v59, 0xffff0000, v71
	v_pk_mul_f32 v[56:57], v[82:83], v[56:57] op_sel_hi:[0,1]
	v_pk_mul_f32 v[58:59], v[82:83], v[58:59] op_sel_hi:[0,1]
	v_pk_mul_f32 v[58:59], v[8:9], v[58:59]
	v_pk_mul_f32 v[56:57], v[6:7], v[56:57]
	global_store_dwordx4 v[68:69], v[56:59], off offset:1024 nt
	s_waitcnt vmcnt(18)
	s_nop 0
	v_lshlrev_b32_e32 v56, 16, v72
	v_and_b32_e32 v57, 0xffff0000, v72
	v_lshlrev_b32_e32 v58, 16, v73
	v_and_b32_e32 v59, 0xffff0000, v73
	v_pk_mul_f32 v[56:57], v[82:83], v[56:57] op_sel_hi:[0,1]
	v_pk_mul_f32 v[58:59], v[82:83], v[58:59] op_sel_hi:[0,1]
	v_pk_mul_f32 v[58:59], v[12:13], v[58:59]
	v_pk_mul_f32 v[56:57], v[10:11], v[56:57]
	global_store_dwordx4 v[68:69], v[56:59], off offset:2048 nt
	s_waitcnt vmcnt(17)
	s_nop 0
	v_mov_b32_e32 v58, v61
	v_mov_b32_e32 v59, v62
	v_mov_b32_e32 v61, v63
	v_pk_add_f32 v[58:59], v[58:59], v[60:61]
	v_lshlrev_b32_e32 v56, 16, v74
	v_add_f32_e32 v60, v58, v59
	ds_bpermute_b32 v61, v55, v60
	v_and_b32_e32 v57, 0xffff0000, v74
	v_lshlrev_b32_e32 v58, 16, v75
	v_and_b32_e32 v59, 0xffff0000, v75
	v_pk_mul_f32 v[56:57], v[82:83], v[56:57] op_sel_hi:[0,1]
	s_waitcnt lgkmcnt(0)
	v_add_f32_e32 v60, v60, v61
	ds_bpermute_b32 v61, v86, v60
	v_pk_mul_f32 v[58:59], v[82:83], v[58:59] op_sel_hi:[0,1]
	v_pk_mul_f32 v[58:59], v[16:17], v[58:59]
	v_pk_mul_f32 v[56:57], v[14:15], v[56:57]
	global_store_dwordx4 v[68:69], v[56:59], off offset:3072 nt
	v_lshl_add_u64 v[62:63], v[0:1], 0, s[14:15]
	s_waitcnt lgkmcnt(0)
	v_add_f32_e32 v56, v60, v61
	v_fmamk_f32 v56, v56, 0x3a800000, v49
	v_rsq_f32_e32 v60, v56
	s_waitcnt vmcnt(17)
	v_lshlrev_b32_e32 v56, 16, v76
	v_and_b32_e32 v57, 0xffff0000, v76
	v_lshlrev_b32_e32 v58, 16, v77
	v_and_b32_e32 v59, 0xffff0000, v77
	v_pk_mul_f32 v[56:57], v[60:61], v[56:57] op_sel_hi:[0,1]
	v_pk_mul_f32 v[58:59], v[60:61], v[58:59] op_sel_hi:[0,1]
	v_pk_mul_f32 v[58:59], v[4:5], v[58:59]
	v_pk_mul_f32 v[56:57], v[2:3], v[56:57]
	global_store_dwordx4 v[62:63], v[56:59], off nt
	s_waitcnt vmcnt(17)
	s_nop 0
	v_lshlrev_b32_e32 v56, 16, v78
	v_and_b32_e32 v57, 0xffff0000, v78
	v_lshlrev_b32_e32 v58, 16, v79
	v_and_b32_e32 v59, 0xffff0000, v79
	v_pk_mul_f32 v[56:57], v[60:61], v[56:57] op_sel_hi:[0,1]
	v_pk_mul_f32 v[58:59], v[60:61], v[58:59] op_sel_hi:[0,1]
	v_pk_mul_f32 v[58:59], v[8:9], v[58:59]
	v_pk_mul_f32 v[56:57], v[6:7], v[56:57]
	global_store_dwordx4 v[62:63], v[56:59], off offset:1024 nt
	s_waitcnt vmcnt(17)
	s_nop 0
	v_lshlrev_b32_e32 v56, 16, v80
	v_and_b32_e32 v57, 0xffff0000, v80
	v_lshlrev_b32_e32 v58, 16, v81
	v_and_b32_e32 v59, 0xffff0000, v81
	v_pk_mul_f32 v[56:57], v[60:61], v[56:57] op_sel_hi:[0,1]
	v_pk_mul_f32 v[58:59], v[60:61], v[58:59] op_sel_hi:[0,1]
	v_pk_mul_f32 v[58:59], v[12:13], v[58:59]
	v_pk_mul_f32 v[56:57], v[10:11], v[56:57]
	global_store_dwordx4 v[62:63], v[56:59], off offset:2048 nt
	s_waitcnt vmcnt(16)
	s_nop 0
	v_mov_b32_e32 v58, v65
	v_mov_b32_e32 v59, v66
	v_mov_b32_e32 v65, v67
	v_pk_add_f32 v[58:59], v[58:59], v[64:65]
	v_lshlrev_b32_e32 v56, 16, v38
	v_add_f32_e32 v58, v58, v59
	ds_bpermute_b32 v59, v55, v58
	v_and_b32_e32 v57, 0xffff0000, v38
	v_pk_mul_f32 v[56:57], v[60:61], v[56:57] op_sel_hi:[0,1]
	v_lshlrev_b32_e32 v38, 16, v39
	v_and_b32_e32 v39, 0xffff0000, v39
	s_waitcnt lgkmcnt(0)
	v_add_f32_e32 v61, v58, v59
	ds_bpermute_b32 v64, v86, v61
	v_pk_mul_f32 v[38:39], v[60:61], v[38:39] op_sel_hi:[0,1]
	v_pk_mul_f32 v[58:59], v[16:17], v[38:39]
	v_pk_mul_f32 v[56:57], v[14:15], v[56:57]
	global_store_dwordx4 v[62:63], v[56:59], off offset:3072 nt
	s_waitcnt lgkmcnt(0)
	v_add_f32_e32 v38, v61, v64
	v_fmamk_f32 v38, v38, 0x3a800000, v49
	v_rsq_f32_e32 v56, v38
	s_waitcnt vmcnt(16)
	v_lshlrev_b32_e32 v38, 16, v40
	v_and_b32_e32 v39, 0xffff0000, v40
	v_lshlrev_b32_e32 v40, 16, v41
	v_and_b32_e32 v41, 0xffff0000, v41
	v_pk_mul_f32 v[38:39], v[56:57], v[38:39] op_sel_hi:[0,1]
	v_pk_mul_f32 v[40:41], v[56:57], v[40:41] op_sel_hi:[0,1]
	v_pk_mul_f32 v[40:41], v[4:5], v[40:41]
	v_pk_mul_f32 v[38:39], v[2:3], v[38:39]
	v_lshl_add_u64 v[58:59], v[0:1], 0, s[12:13]
	global_store_dwordx4 v[58:59], v[38:41], off nt
	s_waitcnt vmcnt(16)
	s_nop 0
	v_lshlrev_b32_e32 v38, 16, v36
	v_and_b32_e32 v39, 0xffff0000, v36
	v_lshlrev_b32_e32 v36, 16, v37
	v_and_b32_e32 v37, 0xffff0000, v37
	v_pk_mul_f32 v[40:41], v[56:57], v[38:39] op_sel_hi:[0,1]
	v_pk_mul_f32 v[36:37], v[56:57], v[36:37] op_sel_hi:[0,1]
	v_pk_mul_f32 v[38:39], v[8:9], v[36:37]
	v_pk_mul_f32 v[36:37], v[6:7], v[40:41]
	global_store_dwordx4 v[58:59], v[36:39], off offset:1024 nt
	s_waitcnt vmcnt(16)
	s_nop 0
	v_lshlrev_b32_e32 v36, 16, v34
	v_and_b32_e32 v37, 0xffff0000, v34
	v_lshlrev_b32_e32 v34, 16, v35
	v_and_b32_e32 v35, 0xffff0000, v35
	v_pk_mul_f32 v[38:39], v[56:57], v[36:37] op_sel_hi:[0,1]
	v_pk_mul_f32 v[34:35], v[56:57], v[34:35] op_sel_hi:[0,1]
	v_pk_mul_f32 v[36:37], v[12:13], v[34:35]
	v_pk_mul_f32 v[34:35], v[10:11], v[38:39]
	global_store_dwordx4 v[58:59], v[34:37], off offset:2048 nt
	s_waitcnt vmcnt(15)
	s_nop 0
	v_mov_b32_e32 v36, v19
	v_mov_b32_e32 v37, v20
	v_mov_b32_e32 v19, v21
	v_pk_add_f32 v[18:19], v[36:37], v[18:19]
	v_lshlrev_b32_e32 v34, 16, v26
	v_add_f32_e32 v20, v18, v19
	ds_bpermute_b32 v21, v55, v20
	v_and_b32_e32 v35, 0xffff0000, v26
	v_lshlrev_b32_e32 v18, 16, v27
	v_and_b32_e32 v19, 0xffff0000, v27
	v_pk_mul_f32 v[26:27], v[56:57], v[34:35] op_sel_hi:[0,1]
	s_waitcnt lgkmcnt(0)
	v_add_f32_e32 v34, v20, v21
	ds_bpermute_b32 v35, v86, v34
	v_pk_mul_f32 v[18:19], v[56:57], v[18:19] op_sel_hi:[0,1]
	v_pk_mul_f32 v[20:21], v[16:17], v[18:19]
	v_pk_mul_f32 v[18:19], v[14:15], v[26:27]
	global_store_dwordx4 v[58:59], v[18:21], off offset:3072 nt
	s_waitcnt lgkmcnt(0)
	s_nop 0
	v_add_f32_e32 v18, v34, v35
	v_fmamk_f32 v18, v18, 0x3a800000, v49
	v_rsq_f32_e32 v26, v18
	s_waitcnt vmcnt(15)
	v_lshlrev_b32_e32 v18, 16, v30
	v_and_b32_e32 v19, 0xffff0000, v30
	v_lshlrev_b32_e32 v20, 16, v31
	v_and_b32_e32 v21, 0xffff0000, v31
	v_pk_mul_f32 v[18:19], v[26:27], v[18:19] op_sel_hi:[0,1]
	v_pk_mul_f32 v[20:21], v[26:27], v[20:21] op_sel_hi:[0,1]
	v_pk_mul_f32 v[20:21], v[4:5], v[20:21]
	v_pk_mul_f32 v[18:19], v[2:3], v[18:19]
	v_lshl_add_u64 v[30:31], v[0:1], 0, s[10:11]
	global_store_dwordx4 v[30:31], v[18:21], off nt
	s_waitcnt vmcnt(15)
	s_nop 0
	v_lshlrev_b32_e32 v18, 16, v32
	v_and_b32_e32 v19, 0xffff0000, v32
	v_lshlrev_b32_e32 v20, 16, v33
	v_and_b32_e32 v21, 0xffff0000, v33
	v_pk_mul_f32 v[18:19], v[26:27], v[18:19] op_sel_hi:[0,1]
	v_pk_mul_f32 v[20:21], v[26:27], v[20:21] op_sel_hi:[0,1]
	v_pk_mul_f32 v[20:21], v[8:9], v[20:21]
	v_pk_mul_f32 v[18:19], v[6:7], v[18:19]
	global_store_dwordx4 v[30:31], v[18:21], off offset:1024 nt
	s_waitcnt vmcnt(15)
	s_nop 0
	v_lshlrev_b32_e32 v18, 16, v28
	v_and_b32_e32 v19, 0xffff0000, v28
	v_lshlrev_b32_e32 v20, 16, v29
	v_and_b32_e32 v21, 0xffff0000, v29
	v_pk_mul_f32 v[18:19], v[26:27], v[18:19] op_sel_hi:[0,1]
	v_pk_mul_f32 v[20:21], v[26:27], v[20:21] op_sel_hi:[0,1]
	v_pk_mul_f32 v[20:21], v[12:13], v[20:21]
	v_pk_mul_f32 v[18:19], v[10:11], v[18:19]
	global_store_dwordx4 v[30:31], v[18:21], off offset:2048 nt
	s_waitcnt vmcnt(15)
	s_nop 0
	v_lshlrev_b32_e32 v18, 16, v24
	v_and_b32_e32 v19, 0xffff0000, v24
	v_lshlrev_b32_e32 v20, 16, v25
	v_and_b32_e32 v21, 0xffff0000, v25
	v_pk_mul_f32 v[18:19], v[26:27], v[18:19] op_sel_hi:[0,1]
	v_pk_mul_f32 v[20:21], v[26:27], v[20:21] op_sel_hi:[0,1]
	v_pk_mul_f32 v[20:21], v[16:17], v[20:21]
	v_pk_mul_f32 v[18:19], v[14:15], v[18:19]
	global_store_dwordx4 v[30:31], v[18:21], off offset:3072 nt

.LBB0_2378:
	s_and_saveexec_b64 s[2:3], s[8:9]
	v_mov_b32_e32 v18, s27
	ds_write_b32 v18, v54
	s_or_b64 exec, exec, s[2:3]
	s_waitcnt lgkmcnt(0)
	s_barrier
	ds_read_b32 v18, v47
	s_waitcnt lgkmcnt(0)
	s_barrier
	v_cmp_le_i32_e64 s[2:3], s28, v18
	v_readfirstlane_b32 s30, v18
	s_and_b64 vcc, exec, s[2:3]
	s_cbranch_vccnz .LBB0_2377
	s_and_saveexec_b64 s[10:11], s[8:9]
	s_cbranch_execz .LBB0_2385
	s_mov_b64 s[14:15], exec
	v_mbcnt_lo_u32_b32 v18, s14, 0
	v_mbcnt_hi_u32_b32 v18, s15, v18
	v_cmp_eq_u32_e32 vcc, 0, v18
	s_and_saveexec_b64 s[12:13], vcc
	s_cbranch_execz .LBB0_2384
	s_bcnt1_i32_b64 s14, s[14:15]
	v_mov_b32_e32 v19, s14
	global_atomic_add v254, v195, v19, s[4:5] sc0
